# bundle + HGRN2 chain prefetch loads via scalar-base addressing (no per-load 64-bit VALU adds) (run 1)
# baseline (speedup 1.0000x reference)
; #define GAS __attribute__((address_space(1)))
; template <int PART>
; __device__ __forceinline__ void prefetch(Pre& P, const GAS unsigned char* ws, size_t row0, int nvalid, int seg, int colb  , int trow  , int sgcol  ) {
;     ...
;     if (nvalid == 64) {
; #pragma unroll
;         for (int i = 0; i < 8; ++i) { const unsigned o = (unsigned)((seg * 8 + i) * 1024 + colb);
;             if (PART & 1) P.lf[i] = *(const GAS unsigned*)(LF + o);
.LBB0_780:
	global_load_dword v95, v90, s[66:67]
	global_load_dword v97, v90, s[66:67] offset:2048
	global_load_dword v99, v88, s[66:67]
	global_load_dword v103, v86, s[66:67]
	global_load_dword v101, v84, s[66:67]
	global_load_dword v117, v82, s[66:67]
	global_load_dword v118, v80, s[66:67]
	s_mov_b64 s[68:69], -1
	v_mov_b64_e32 v[0:1], v[78:79]

; #define GAS __attribute__((address_space(1)))
; template <int PART>
; __device__ __forceinline__ void prefetch(Pre& P, const GAS unsigned char* ws, size_t row0, int nvalid, int seg, int colb  , int trow  , int sgcol  ) {
;     ...
;     if (nvalid == 64) {
; #pragma unroll
;         for (int i = 0; i < 8; ++i) { const unsigned o = (unsigned)((seg * 8 + i) * 1024 + colb);
;             if (PART & 1) P.lf[i] = *(const GAS unsigned*)(LF + o);
;             if (PART & 2) { P.q[i] = *(const GAS unsigned*)(QC + o); P.k[i] = *(const GAS unsigned*)(KC + o); P.v[i] = *(const GAS unsigned*)(IC + o); } }
;     } else {
; #pragma unroll
;         for (int i = 0; i < 8; ++i) { const int t = seg * 8 + i; const unsigned o = (unsigned)(t * 1024 + colb);
;             if (t < nvalid) { if (PART & 1) P.lf[i] = *(const GAS unsigned*)(LF + o); if (PART & 2) { P.q[i] = *(const GAS unsigned*)(QC + o); P.k[i] = *(const GAS unsigned*)(KC + o); P.v[i] = *(const GAS unsigned*)(IC + o); } }
;             else { if (PART & 1) P.lf[i] = 0u; if (PART & 2) { P.q[i] = 0u; P.k[i] = 0u; P.v[i] = 0u; } } }
.LBB0_803:
	s_mov_b64 s[70:71], 0
	v_mov_b64_e32 v[0:1], v[104:105]
	s_cbranch_execz .LBB0_805
	global_load_dword v120, v90, s[68:69]
	global_load_dword v121, v90, s[66:67]
	global_load_dword v122, v90, s[64:65]
	global_load_dword v119, v90, s[68:69] offset:2048
	global_load_dword v124, v90, s[66:67] offset:2048
	global_load_dword v123, v90, s[64:65] offset:2048
	global_load_dword v125, v88, s[68:69]
	global_load_dword v126, v88, s[66:67]
	global_load_dword v127, v88, s[64:65]
	global_load_dword v128, v86, s[68:69]
	global_load_dword v131, v86, s[66:67]
	global_load_dword v130, v86, s[64:65]
	global_load_dword v134, v84, s[68:69]
	global_load_dword v133, v84, s[66:67]
	global_load_dword v132, v84, s[64:65]
	global_load_dword v135, v82, s[68:69]
	global_load_dword v137, v82, s[66:67]
	global_load_dword v136, v82, s[64:65]
	global_load_dword v138, v80, s[68:69]
	global_load_dword v139, v80, s[66:67]
	global_load_dword v140, v80, s[64:65]
	s_mov_b64 s[70:71], -1
	v_mov_b64_e32 v[0:1], v[78:79]
.LBB0_805:
	v_mov_b32_e32 v143, 0
	s_andn2_b64 vcc, exec, s[70:71]
	v_mov_b32_e32 v142, 0
	v_mov_b32_e32 v141, 0
	s_cbranch_vccnz .LBB0_807
	v_lshlrev_b64 v[0:1], 1, v[0:1]
	global_load_dword v141, v0, s[68:69]
	global_load_dword v142, v0, s[66:67]
	global_load_dword v143, v0, s[64:65]
